# v38 + first K-loop half-iteration peeled in all three GEMM bodies: accumulators start from MFMA C=0, per-unit accumulator zeroing removed
# speedup vs baseline: 1.0158x; 1.0033x over previous
.LBB0_306:
	s_ashr_i32 s51, s50, 31
	s_lshl_b64 s[12:13], s[50:51], 19
	s_add_u32 s52, s8, s12
	s_addc_u32 s53, s9, s13
	s_and_b64 s[12:13], s[38:39], exec
	s_cselect_b32 s73, s53, s57
	s_cselect_b32 s74, s52, s56
	s_ashr_i32 s49, s48, 31
	s_lshl_b64 s[12:13], s[48:49], 19
	s_add_u32 s54, s2, s12
	s_addc_u32 s55, s16, s13
	s_and_b64 s[12:13], s[38:39], exec
	s_cselect_b32 s75, s55, s59
	s_cselect_b32 s76, s54, s58
	s_lshl_b64 s[12:13], s[50:51], 11
	v_lshl_add_u64 v[50:51], v[166:167], 0, s[12:13]
	s_lshl_b32 s12, s71, 12
	s_and_b32 s51, s12, 0x1000
	s_lshl_b64 s[12:13], s[48:49], 10
	s_add_u32 s56, s56, 0x40080
	s_addc_u32 s57, s57, 0
	v_lshl_add_u64 v[52:53], v[168:169], 0, s[12:13]
	s_add_u32 s12, s58, 0x100
	s_addc_u32 s13, s59, 0
	s_add_i32 s51, s23, s51
	s_mov_b32 s49, -2
	s_add_i32 s77, s51, 0x800
	s_mov_b64 s[58:59], 0
	s_add_u32 s60, s56, 0xfffc0080
	s_addc_u32 s61, s57, -1
	s_and_b64 s[58:59], s[58:59], exec
	s_cselect_b32 s61, s73, s61
	s_cselect_b32 s60, s74, s60
	s_cselect_b32 s59, s75, s13
	s_cselect_b32 s58, s76, s12
	s_add_i32 s80, 0, 0x10000
	s_add_i32 s82, 0, 0x14000
	v_add_u32_e32 v146, s80, v165
	v_add_u32_e32 v182, s82, v165
	ds_read_b128 v[54:57], v146
	ds_read_b128 v[66:69], v146 offset:1024
	ds_read_b128 v[70:73], v146 offset:2048
	ds_read_b128 v[146:149], v146 offset:3072
	ds_read_b128 v[150:153], v182
	ds_read_b128 v[174:177], v182 offset:1024
	ds_read_b128 v[178:181], v182 offset:2048
	ds_read_b128 v[182:185], v182 offset:3072
	v_lshl_add_u64 v[224:225], s[56:57], 0, v[170:171]
	s_add_i32 m0, s64, 0xc000
	ds_read_b128 v[190:193], v188
	ds_read_b128 v[194:197], v188 offset:1024
	ds_read_b128 v[198:201], v188 offset:2048
	ds_read_b128 v[202:205], v188 offset:3072
	ds_read_b128 v[208:211], v188 offset:4096
	ds_read_b128 v[212:215], v188 offset:5120
	ds_read_b128 v[216:219], v188 offset:6144
	ds_read_b128 v[220:223], v188 offset:7168
	global_load_lds_dwordx4 v[224:225], off
	v_lshl_add_u64 v[224:225], s[56:57], 0, v[172:173]
	s_add_i32 m0, s64, 0xe000
	s_nop 0
	global_load_lds_dwordx4 v[224:225], off
	s_waitcnt vmcnt(8)
	s_waitcnt lgkmcnt(0)
	s_barrier
	s_setprio 1
	s_waitcnt lgkmcnt(0)
	v_mfma_f32_16x16x32_bf16 v[142:145], v[54:57], v[190:193], 0
	v_mfma_f32_16x16x32_bf16 v[134:137], v[70:73], v[190:193], 0
	v_mfma_f32_16x16x32_bf16 v[126:129], v[54:57], v[198:201], 0
	v_mfma_f32_16x16x32_bf16 v[118:121], v[70:73], v[198:201], 0
	v_mfma_f32_16x16x32_bf16 v[110:113], v[54:57], v[208:211], 0
	v_mfma_f32_16x16x32_bf16 v[102:105], v[70:73], v[208:211], 0
	v_mfma_f32_16x16x32_bf16 v[94:97], v[54:57], v[216:219], 0
	v_mfma_f32_16x16x32_bf16 v[86:89], v[70:73], v[216:219], 0
	v_mfma_f32_16x16x32_bf16 v[142:145], v[66:69], v[194:197], v[142:145]
	v_mfma_f32_16x16x32_bf16 v[134:137], v[146:149], v[194:197], v[134:137]
	v_mfma_f32_16x16x32_bf16 v[126:129], v[66:69], v[202:205], v[126:129]
	v_mfma_f32_16x16x32_bf16 v[118:121], v[146:149], v[202:205], v[118:121]
	v_mfma_f32_16x16x32_bf16 v[110:113], v[66:69], v[212:215], v[110:113]
	v_mfma_f32_16x16x32_bf16 v[102:105], v[146:149], v[212:215], v[102:105]
	v_mfma_f32_16x16x32_bf16 v[94:97], v[66:69], v[220:223], v[94:97]
	v_mfma_f32_16x16x32_bf16 v[86:89], v[146:149], v[220:223], v[86:89]
	s_setprio 0
	s_setprio 1
	v_mfma_f32_16x16x32_bf16 v[138:141], v[150:153], v[190:193], 0
	v_mfma_f32_16x16x32_bf16 v[130:133], v[178:181], v[190:193], 0
	v_mfma_f32_16x16x32_bf16 v[122:125], v[150:153], v[198:201], 0
	v_mfma_f32_16x16x32_bf16 v[114:117], v[178:181], v[198:201], 0
	v_mfma_f32_16x16x32_bf16 v[106:109], v[150:153], v[208:211], 0
	v_mfma_f32_16x16x32_bf16 v[98:101], v[178:181], v[208:211], 0
	v_mfma_f32_16x16x32_bf16 v[90:93], v[150:153], v[216:219], 0
	v_mfma_f32_16x16x32_bf16 v[82:85], v[178:181], v[216:219], 0
	v_mfma_f32_16x16x32_bf16 v[138:141], v[174:177], v[194:197], v[138:141]
	v_mfma_f32_16x16x32_bf16 v[130:133], v[182:185], v[194:197], v[130:133]
	v_mfma_f32_16x16x32_bf16 v[122:125], v[174:177], v[202:205], v[122:125]
	v_mfma_f32_16x16x32_bf16 v[114:117], v[182:185], v[202:205], v[114:117]
	v_mfma_f32_16x16x32_bf16 v[106:109], v[174:177], v[212:215], v[106:109]
	v_mfma_f32_16x16x32_bf16 v[98:101], v[182:185], v[212:215], v[98:101]
	v_mfma_f32_16x16x32_bf16 v[90:93], v[174:177], v[220:223], v[90:93]
	v_mfma_f32_16x16x32_bf16 v[82:85], v[182:185], v[220:223], v[82:85]
	s_setprio 0
	s_barrier
	s_add_i32 s80, s80, s22
	v_lshl_add_u64 v[224:225], s[58:59], 0, v[158:159]
	s_mov_b32 m0, s80
	ds_read_b128 v[190:193], v188 offset:16384
	ds_read_b128 v[194:197], v188 offset:17408
	ds_read_b128 v[198:201], v188 offset:18432
	ds_read_b128 v[202:205], v188 offset:19456
	ds_read_b128 v[208:211], v188 offset:20480
	ds_read_b128 v[212:215], v188 offset:21504
	ds_read_b128 v[216:219], v188 offset:22528
	ds_read_b128 v[220:223], v188 offset:23552
	global_load_lds_dwordx4 v[224:225], off
	s_add_i32 m0, s80, 0x2000
	s_add_u32 s80, s58, 0x40000
	v_lshl_add_u64 v[226:227], s[58:59], 0, v[154:155]
	s_addc_u32 s81, s59, 0
	s_add_i32 s82, s82, s22
	global_load_lds_dwordx4 v[226:227], off
	v_lshl_add_u64 v[228:229], s[80:81], 0, v[158:159]
	s_mov_b32 m0, s82
	v_lshl_add_u64 v[230:231], s[60:61], 0, v[156:157]
	global_load_lds_dwordx4 v[228:229], off
	v_lshl_add_u64 v[228:229], s[80:81], 0, v[154:155]
	s_add_i32 m0, s82, 0x2000
	s_nop 0
	global_load_lds_dwordx4 v[228:229], off
	v_lshl_add_u64 v[228:229], s[60:61], 0, v[160:161]
	s_mov_b32 m0, s64
	s_nop 0
	global_load_lds_dwordx4 v[228:229], off
	s_mov_b32 m0, s65
	s_nop 0
	global_load_lds_dwordx4 v[230:231], off
	s_waitcnt vmcnt(8)
	s_waitcnt lgkmcnt(0)
	s_barrier
	s_setprio 1
	s_waitcnt lgkmcnt(0)
	v_mfma_f32_16x16x32_bf16 v[78:81], v[54:57], v[190:193], 0
	v_mfma_f32_16x16x32_bf16 v[62:65], v[70:73], v[190:193], 0
	v_mfma_f32_16x16x32_bf16 v[46:49], v[54:57], v[198:201], 0
	v_mfma_f32_16x16x32_bf16 v[38:41], v[70:73], v[198:201], 0
	v_mfma_f32_16x16x32_bf16 v[30:33], v[54:57], v[208:211], 0
	v_mfma_f32_16x16x32_bf16 v[22:25], v[70:73], v[208:211], 0
	v_mfma_f32_16x16x32_bf16 v[14:17], v[54:57], v[216:219], 0
	v_mfma_f32_16x16x32_bf16 v[6:9], v[70:73], v[216:219], 0
	v_mfma_f32_16x16x32_bf16 v[78:81], v[66:69], v[194:197], v[78:81]
	v_mfma_f32_16x16x32_bf16 v[62:65], v[146:149], v[194:197], v[62:65]
	v_mfma_f32_16x16x32_bf16 v[46:49], v[66:69], v[202:205], v[46:49]
	v_mfma_f32_16x16x32_bf16 v[38:41], v[146:149], v[202:205], v[38:41]
	v_mfma_f32_16x16x32_bf16 v[30:33], v[66:69], v[212:215], v[30:33]
	v_mfma_f32_16x16x32_bf16 v[22:25], v[146:149], v[212:215], v[22:25]
	v_mfma_f32_16x16x32_bf16 v[14:17], v[66:69], v[220:223], v[14:17]
	v_mfma_f32_16x16x32_bf16 v[6:9], v[146:149], v[220:223], v[6:9]
	s_setprio 0
	s_setprio 1
	v_mfma_f32_16x16x32_bf16 v[58:61], v[178:181], v[190:193], 0
	v_mfma_f32_16x16x32_bf16 v[42:45], v[150:153], v[198:201], 0
	v_mfma_f32_16x16x32_bf16 v[34:37], v[178:181], v[198:201], 0
	v_mfma_f32_16x16x32_bf16 v[26:29], v[150:153], v[208:211], 0
	v_mfma_f32_16x16x32_bf16 v[18:21], v[178:181], v[208:211], 0
	v_mfma_f32_16x16x32_bf16 v[10:13], v[150:153], v[216:219], 0
	v_mfma_f32_16x16x32_bf16 v[2:5], v[178:181], v[216:219], 0
	v_mfma_f32_16x16x32_bf16 v[54:57], v[150:153], v[190:193], 0
	v_mfma_f32_16x16x32_bf16 v[58:61], v[182:185], v[194:197], v[58:61]
	v_mfma_f32_16x16x32_bf16 v[42:45], v[174:177], v[202:205], v[42:45]
	v_mfma_f32_16x16x32_bf16 v[34:37], v[182:185], v[202:205], v[34:37]
	v_mfma_f32_16x16x32_bf16 v[26:29], v[174:177], v[212:215], v[26:29]
	v_mfma_f32_16x16x32_bf16 v[18:21], v[182:185], v[212:215], v[18:21]
	v_mfma_f32_16x16x32_bf16 v[10:13], v[174:177], v[220:223], v[10:13]
	v_mfma_f32_16x16x32_bf16 v[2:5], v[182:185], v[220:223], v[2:5]
	v_mfma_f32_16x16x32_bf16 v[54:57], v[174:177], v[194:197], v[54:57]
	s_setprio 0
	s_barrier
	s_branch .Lpeel_mid_sw

.Lpeel_mid_sw:
	s_add_i32 s80, 0, 0x18000
	s_add_i32 s81, 0, 0x1c000
	v_add_u32_e32 v146, s80, v165
	v_add_u32_e32 v182, s81, v165
	ds_read_b128 v[66:69], v146
	ds_read_b128 v[70:73], v146 offset:1024
	ds_read_b128 v[74:77], v146 offset:2048
	ds_read_b128 v[146:149], v146 offset:3072
	ds_read_b128 v[150:153], v182
	ds_read_b128 v[174:177], v182 offset:1024
	ds_read_b128 v[178:181], v182 offset:2048
	ds_read_b128 v[182:185], v182 offset:3072
	s_add_u32 s60, s60, 0x40000
	s_addc_u32 s61, s61, 0
	s_mov_b32 m0, s66
	v_lshl_add_u64 v[232:233], s[60:61], 0, v[160:161]
	ds_read_b128 v[190:193], v188 offset:32768
	ds_read_b128 v[194:197], v188 offset:33792
	ds_read_b128 v[198:201], v188 offset:34816
	ds_read_b128 v[202:205], v188 offset:35840
	ds_read_b128 v[208:211], v188 offset:36864
	ds_read_b128 v[212:215], v188 offset:37888
	ds_read_b128 v[216:219], v188 offset:38912
	ds_read_b128 v[220:223], v188 offset:39936
	global_load_lds_dwordx4 v[232:233], off
	v_lshl_add_u64 v[232:233], s[60:61], 0, v[156:157]
	s_mov_b32 m0, s67
	s_nop 0
	global_load_lds_dwordx4 v[232:233], off
	s_waitcnt vmcnt(8)
	s_waitcnt lgkmcnt(0)
	s_barrier
	s_setprio 1
	s_waitcnt lgkmcnt(0)
	v_mfma_f32_16x16x32_bf16 v[142:145], v[66:69], v[190:193], v[142:145]
	v_mfma_f32_16x16x32_bf16 v[134:137], v[74:77], v[190:193], v[134:137]
	v_mfma_f32_16x16x32_bf16 v[126:129], v[66:69], v[198:201], v[126:129]
	v_mfma_f32_16x16x32_bf16 v[118:121], v[74:77], v[198:201], v[118:121]
	v_mfma_f32_16x16x32_bf16 v[110:113], v[66:69], v[208:211], v[110:113]
	v_mfma_f32_16x16x32_bf16 v[102:105], v[74:77], v[208:211], v[102:105]
	v_mfma_f32_16x16x32_bf16 v[94:97], v[66:69], v[216:219], v[94:97]
	v_mfma_f32_16x16x32_bf16 v[86:89], v[74:77], v[216:219], v[86:89]
	v_mfma_f32_16x16x32_bf16 v[142:145], v[70:73], v[194:197], v[142:145]
	v_mfma_f32_16x16x32_bf16 v[134:137], v[146:149], v[194:197], v[134:137]
	v_mfma_f32_16x16x32_bf16 v[126:129], v[70:73], v[202:205], v[126:129]
	v_mfma_f32_16x16x32_bf16 v[118:121], v[146:149], v[202:205], v[118:121]
	v_mfma_f32_16x16x32_bf16 v[110:113], v[70:73], v[212:215], v[110:113]
	v_mfma_f32_16x16x32_bf16 v[102:105], v[146:149], v[212:215], v[102:105]
	v_mfma_f32_16x16x32_bf16 v[94:97], v[70:73], v[220:223], v[94:97]
	v_mfma_f32_16x16x32_bf16 v[86:89], v[146:149], v[220:223], v[86:89]
	s_setprio 0
	s_setprio 1
	v_mfma_f32_16x16x32_bf16 v[138:141], v[150:153], v[190:193], v[138:141]
	v_mfma_f32_16x16x32_bf16 v[130:133], v[178:181], v[190:193], v[130:133]
	v_mfma_f32_16x16x32_bf16 v[122:125], v[150:153], v[198:201], v[122:125]
	v_mfma_f32_16x16x32_bf16 v[114:117], v[178:181], v[198:201], v[114:117]
	v_mfma_f32_16x16x32_bf16 v[106:109], v[150:153], v[208:211], v[106:109]
	v_mfma_f32_16x16x32_bf16 v[98:101], v[178:181], v[208:211], v[98:101]
	v_mfma_f32_16x16x32_bf16 v[90:93], v[150:153], v[216:219], v[90:93]
	v_mfma_f32_16x16x32_bf16 v[82:85], v[178:181], v[216:219], v[82:85]
	v_mfma_f32_16x16x32_bf16 v[138:141], v[174:177], v[194:197], v[138:141]
	v_mfma_f32_16x16x32_bf16 v[130:133], v[182:185], v[194:197], v[130:133]
	v_mfma_f32_16x16x32_bf16 v[122:125], v[174:177], v[202:205], v[122:125]
	v_mfma_f32_16x16x32_bf16 v[114:117], v[182:185], v[202:205], v[114:117]
	v_mfma_f32_16x16x32_bf16 v[106:109], v[174:177], v[212:215], v[106:109]
	v_mfma_f32_16x16x32_bf16 v[98:101], v[182:185], v[212:215], v[98:101]
	v_mfma_f32_16x16x32_bf16 v[90:93], v[174:177], v[220:223], v[90:93]
	v_mfma_f32_16x16x32_bf16 v[82:85], v[182:185], v[220:223], v[82:85]
	s_setprio 0
	s_barrier
	s_add_i32 s60, s80, s22
	v_lshl_add_u64 v[224:225], v[224:225], 0, s[0:1]
	s_mov_b32 m0, s60
	ds_read_b128 v[190:193], v188 offset:49152
	ds_read_b128 v[194:197], v188 offset:50176
	ds_read_b128 v[198:201], v188 offset:51200
	ds_read_b128 v[202:205], v188 offset:52224
	ds_read_b128 v[208:211], v188 offset:53248
	ds_read_b128 v[212:215], v188 offset:54272
	ds_read_b128 v[216:219], v188 offset:55296
	ds_read_b128 v[220:223], v188 offset:56320
	global_load_lds_dwordx4 v[224:225], off
	s_add_i32 m0, s60, 0x2000
	s_add_u32 s58, s58, 0x40080
	v_lshl_add_u64 v[224:225], v[226:227], 0, s[0:1]
	s_addc_u32 s59, s59, 0
	s_add_i32 s60, s81, s22
	global_load_lds_dwordx4 v[224:225], off
	v_lshl_add_u64 v[224:225], s[58:59], 0, v[158:159]
	s_mov_b32 m0, s60
	s_nop 0
	global_load_lds_dwordx4 v[224:225], off
	v_lshl_add_u64 v[224:225], s[58:59], 0, v[154:155]
	s_add_i32 m0, s60, 0x2000
	s_nop 0
	global_load_lds_dwordx4 v[224:225], off
	v_lshl_add_u64 v[224:225], v[228:229], 0, s[0:1]
	s_mov_b32 m0, s69
	s_nop 0
	global_load_lds_dwordx4 v[224:225], off
	v_lshl_add_u64 v[224:225], v[230:231], 0, s[0:1]
	s_mov_b32 m0, s70
	s_nop 0
	global_load_lds_dwordx4 v[224:225], off
	s_waitcnt vmcnt(8)
	s_waitcnt lgkmcnt(0)
	s_barrier
	s_setprio 1
	s_waitcnt lgkmcnt(0)
	v_mfma_f32_16x16x32_bf16 v[78:81], v[66:69], v[190:193], v[78:81]
	v_mfma_f32_16x16x32_bf16 v[62:65], v[74:77], v[190:193], v[62:65]
	v_mfma_f32_16x16x32_bf16 v[46:49], v[66:69], v[198:201], v[46:49]
	v_mfma_f32_16x16x32_bf16 v[38:41], v[74:77], v[198:201], v[38:41]
	v_mfma_f32_16x16x32_bf16 v[30:33], v[66:69], v[208:211], v[30:33]
	v_mfma_f32_16x16x32_bf16 v[22:25], v[74:77], v[208:211], v[22:25]
	v_mfma_f32_16x16x32_bf16 v[14:17], v[66:69], v[216:219], v[14:17]
	v_mfma_f32_16x16x32_bf16 v[6:9], v[74:77], v[216:219], v[6:9]
	v_mfma_f32_16x16x32_bf16 v[78:81], v[70:73], v[194:197], v[78:81]
	v_mfma_f32_16x16x32_bf16 v[62:65], v[146:149], v[194:197], v[62:65]
	v_mfma_f32_16x16x32_bf16 v[46:49], v[70:73], v[202:205], v[46:49]
	v_mfma_f32_16x16x32_bf16 v[38:41], v[146:149], v[202:205], v[38:41]
	v_mfma_f32_16x16x32_bf16 v[30:33], v[70:73], v[212:215], v[30:33]
	v_mfma_f32_16x16x32_bf16 v[22:25], v[146:149], v[212:215], v[22:25]
	v_mfma_f32_16x16x32_bf16 v[14:17], v[70:73], v[220:223], v[14:17]
	v_mfma_f32_16x16x32_bf16 v[6:9], v[146:149], v[220:223], v[6:9]
	s_setprio 0
	s_setprio 1
	v_mfma_f32_16x16x32_bf16 v[54:57], v[150:153], v[190:193], v[54:57]
	v_mfma_f32_16x16x32_bf16 v[74:77], v[174:177], v[194:197], v[54:57]
	v_mfma_f32_16x16x32_bf16 v[54:57], v[178:181], v[190:193], v[58:61]
	v_mfma_f32_16x16x32_bf16 v[42:45], v[150:153], v[198:201], v[42:45]
	v_mfma_f32_16x16x32_bf16 v[34:37], v[178:181], v[198:201], v[34:37]
	v_mfma_f32_16x16x32_bf16 v[26:29], v[150:153], v[208:211], v[26:29]
	v_mfma_f32_16x16x32_bf16 v[18:21], v[178:181], v[208:211], v[18:21]
	v_mfma_f32_16x16x32_bf16 v[10:13], v[150:153], v[216:219], v[10:13]
	v_mfma_f32_16x16x32_bf16 v[2:5], v[178:181], v[216:219], v[2:5]
	v_mfma_f32_16x16x32_bf16 v[58:61], v[182:185], v[194:197], v[54:57]
	v_mfma_f32_16x16x32_bf16 v[42:45], v[174:177], v[202:205], v[42:45]
	v_mfma_f32_16x16x32_bf16 v[34:37], v[182:185], v[202:205], v[34:37]
	v_mfma_f32_16x16x32_bf16 v[26:29], v[174:177], v[212:215], v[26:29]
	v_mfma_f32_16x16x32_bf16 v[18:21], v[182:185], v[212:215], v[18:21]
	v_mfma_f32_16x16x32_bf16 v[10:13], v[174:177], v[220:223], v[10:13]
	v_mfma_f32_16x16x32_bf16 v[2:5], v[182:185], v[220:223], v[2:5]
	s_setprio 0
	s_barrier
	s_add_i32 s49, s49, 2
	s_add_u32 s56, s56, 0x100
	s_addc_u32 s57, s57, 0
	s_add_u32 s12, s12, 0x100
	s_addc_u32 s13, s13, 0
	s_cmp_gt_u32 s49, 13
	s_cbranch_scc1 .LBB0_310

.LBB0_387:
	s_ashr_i32 s65, s64, 31
	s_lshl_b64 s[12:13], s[64:65], 11
	v_lshl_add_u64 v[130:131], v[174:175], 0, s[12:13]
	s_lshl_b32 s12, s57, 12
	s_add_i32 s69, s90, -2
	s_and_b32 s65, s12, 0x1000
	s_lshl_b64 s[12:13], s[66:67], 10
	s_add_u32 s74, s74, 0x80
	s_addc_u32 s75, s75, 0
	s_add_u32 s67, s76, 0x100
	s_waitcnt lgkmcnt(0)
	v_lshl_add_u64 v[132:133], v[176:177], 0, s[12:13]
	s_addc_u32 s73, s77, 0
	s_mov_b32 s12, 0
	s_mov_b64 s[76:77], 0
	s_add_i32 s12, s12, 2
	s_add_u32 s13, s74, 0x80
	s_addc_u32 vcc_lo, s75, 0
	s_and_b64 s[76:77], s[76:77], exec
	s_cselect_b32 s77, s71, vcc_lo
	s_cselect_b32 s76, s70, s13
	s_cselect_b32 vcc_hi, s45, s73
	s_cselect_b32 vcc_lo, s44, s67
	s_add_i32 s13, 0, 0x10000
	v_add_u32_e32 v1, s13, v208
	s_add_i32 s88, 0, 0x14000
	ds_read_b128 v[134:137], v1
	ds_read_b128 v[138:141], v1 offset:1024
	ds_read_b128 v[142:145], v1 offset:2048
	ds_read_b128 v[146:149], v1 offset:3072
	v_add_u32_e32 v1, s88, v208
	ds_read_b128 v[150:153], v1
	ds_read_b128 v[154:157], v1 offset:1024
	ds_read_b128 v[158:161], v1 offset:2048
	ds_read_b128 v[182:185], v1 offset:3072
	v_lshl_add_u64 v[224:225], s[74:75], 0, v[178:179]
	s_add_i32 m0, s80, 0xc000
	ds_read_b128 v[186:189], v211
	ds_read_b128 v[190:193], v211 offset:1024
	ds_read_b128 v[194:197], v211 offset:2048
	ds_read_b128 v[198:201], v211 offset:3072
	ds_read_b128 v[202:205], v211 offset:4096
	ds_read_b128 v[212:215], v211 offset:5120
	ds_read_b128 v[216:219], v211 offset:6144
	ds_read_b128 v[220:223], v211 offset:7168
	global_load_lds_dwordx4 v[224:225], off
	v_lshl_add_u64 v[224:225], s[74:75], 0, v[180:181]
	s_add_i32 m0, s80, 0xe000
	s_nop 0
	global_load_lds_dwordx4 v[224:225], off
	s_waitcnt vmcnt(8)
	s_waitcnt lgkmcnt(0)
	s_barrier
	s_setprio 1
	s_waitcnt lgkmcnt(0)
	v_mfma_f32_16x16x32_bf16 v[126:129], v[134:137], v[186:189], 0
	v_mfma_f32_16x16x32_bf16 v[122:125], v[142:145], v[186:189], 0
	v_mfma_f32_16x16x32_bf16 v[118:121], v[134:137], v[194:197], 0
	v_mfma_f32_16x16x32_bf16 v[114:117], v[142:145], v[194:197], 0
	v_mfma_f32_16x16x32_bf16 v[102:105], v[134:137], v[202:205], 0
	v_mfma_f32_16x16x32_bf16 v[98:101], v[142:145], v[202:205], 0
	v_mfma_f32_16x16x32_bf16 v[86:89], v[134:137], v[216:219], 0
	v_mfma_f32_16x16x32_bf16 v[82:85], v[142:145], v[216:219], 0
	v_mfma_f32_16x16x32_bf16 v[126:129], v[138:141], v[190:193], v[126:129]
	v_mfma_f32_16x16x32_bf16 v[122:125], v[146:149], v[190:193], v[122:125]
	v_mfma_f32_16x16x32_bf16 v[118:121], v[138:141], v[198:201], v[118:121]
	v_mfma_f32_16x16x32_bf16 v[114:117], v[146:149], v[198:201], v[114:117]
	v_mfma_f32_16x16x32_bf16 v[102:105], v[138:141], v[212:215], v[102:105]
	v_mfma_f32_16x16x32_bf16 v[98:101], v[146:149], v[212:215], v[98:101]
	v_mfma_f32_16x16x32_bf16 v[86:89], v[138:141], v[220:223], v[86:89]
	v_mfma_f32_16x16x32_bf16 v[82:85], v[146:149], v[220:223], v[82:85]
	s_setprio 0
	s_setprio 1
	v_mfma_f32_16x16x32_bf16 v[110:113], v[150:153], v[186:189], 0
	v_mfma_f32_16x16x32_bf16 v[106:109], v[158:161], v[186:189], 0
	v_mfma_f32_16x16x32_bf16 v[94:97], v[150:153], v[194:197], 0
	v_mfma_f32_16x16x32_bf16 v[90:93], v[158:161], v[194:197], 0
	v_mfma_f32_16x16x32_bf16 v[78:81], v[150:153], v[202:205], 0
	v_mfma_f32_16x16x32_bf16 v[74:77], v[158:161], v[202:205], 0
	v_mfma_f32_16x16x32_bf16 v[70:73], v[150:153], v[216:219], 0
	v_mfma_f32_16x16x32_bf16 v[66:69], v[158:161], v[216:219], 0
	v_mfma_f32_16x16x32_bf16 v[110:113], v[154:157], v[190:193], v[110:113]
	v_mfma_f32_16x16x32_bf16 v[106:109], v[182:185], v[190:193], v[106:109]
	v_mfma_f32_16x16x32_bf16 v[94:97], v[154:157], v[198:201], v[94:97]
	v_mfma_f32_16x16x32_bf16 v[90:93], v[182:185], v[198:201], v[90:93]
	v_mfma_f32_16x16x32_bf16 v[78:81], v[154:157], v[212:215], v[78:81]
	v_mfma_f32_16x16x32_bf16 v[74:77], v[182:185], v[212:215], v[74:77]
	v_mfma_f32_16x16x32_bf16 v[70:73], v[154:157], v[220:223], v[70:73]
	v_mfma_f32_16x16x32_bf16 v[66:69], v[182:185], v[220:223], v[66:69]
	s_setprio 0
	s_barrier
	s_add_i32 s13, s13, s97
	v_lshl_add_u64 v[224:225], vcc, 0, v[168:169]
	s_mov_b32 m0, s13
	ds_read_b128 v[186:189], v211 offset:16384
	ds_read_b128 v[190:193], v211 offset:17408
	ds_read_b128 v[194:197], v211 offset:18432
	ds_read_b128 v[198:201], v211 offset:19456
	ds_read_b128 v[202:205], v211 offset:20480
	ds_read_b128 v[212:215], v211 offset:21504
	ds_read_b128 v[216:219], v211 offset:22528
	ds_read_b128 v[220:223], v211 offset:23552
	global_load_lds_dwordx4 v[224:225], off
	s_add_i32 m0, s13, 0x2000
	v_lshl_add_u64 v[226:227], vcc, 0, v[172:173]
	s_add_u32 vcc_lo, vcc_lo, s59
	s_addc_u32 vcc_hi, vcc_hi, 0
	s_add_i32 s13, s88, s97
	global_load_lds_dwordx4 v[226:227], off
	v_lshl_add_u64 v[228:229], vcc, 0, v[168:169]
	s_mov_b32 m0, s13
	v_lshl_add_u64 v[230:231], vcc, 0, v[172:173]
	global_load_lds_dwordx4 v[228:229], off
	s_add_i32 m0, s13, 0x2000
	v_lshl_add_u64 v[232:233], s[76:77], 0, v[166:167]
	global_load_lds_dwordx4 v[230:231], off
	s_mov_b32 m0, s80
	v_lshl_add_u64 v[242:243], s[76:77], 0, v[170:171]
	global_load_lds_dwordx4 v[232:233], off
	s_mov_b32 m0, s60
	s_nop 0
	global_load_lds_dwordx4 v[242:243], off
	s_waitcnt vmcnt(8)
	s_waitcnt lgkmcnt(0)
	s_barrier
	s_setprio 1
	s_waitcnt lgkmcnt(0)
	v_mfma_f32_16x16x32_bf16 v[62:65], v[134:137], v[186:189], 0
	v_mfma_f32_16x16x32_bf16 v[58:61], v[142:145], v[186:189], 0
	v_mfma_f32_16x16x32_bf16 v[54:57], v[134:137], v[194:197], 0
	v_mfma_f32_16x16x32_bf16 v[50:53], v[142:145], v[194:197], 0
	v_mfma_f32_16x16x32_bf16 v[38:41], v[134:137], v[202:205], 0
	v_mfma_f32_16x16x32_bf16 v[34:37], v[142:145], v[202:205], 0
	v_mfma_f32_16x16x32_bf16 v[22:25], v[134:137], v[216:219], 0
	v_mfma_f32_16x16x32_bf16 v[18:21], v[142:145], v[216:219], 0
	v_mfma_f32_16x16x32_bf16 v[62:65], v[138:141], v[190:193], v[62:65]
	v_mfma_f32_16x16x32_bf16 v[58:61], v[146:149], v[190:193], v[58:61]
	v_mfma_f32_16x16x32_bf16 v[54:57], v[138:141], v[198:201], v[54:57]
	v_mfma_f32_16x16x32_bf16 v[50:53], v[146:149], v[198:201], v[50:53]
	v_mfma_f32_16x16x32_bf16 v[38:41], v[138:141], v[212:215], v[38:41]
	v_mfma_f32_16x16x32_bf16 v[34:37], v[146:149], v[212:215], v[34:37]
	v_mfma_f32_16x16x32_bf16 v[22:25], v[138:141], v[220:223], v[22:25]
	v_mfma_f32_16x16x32_bf16 v[18:21], v[146:149], v[220:223], v[18:21]
	s_setprio 0
	s_setprio 1
	v_mfma_f32_16x16x32_bf16 v[46:49], v[150:153], v[186:189], 0
	v_mfma_f32_16x16x32_bf16 v[42:45], v[158:161], v[186:189], 0
	v_mfma_f32_16x16x32_bf16 v[30:33], v[150:153], v[194:197], 0
	v_mfma_f32_16x16x32_bf16 v[26:29], v[158:161], v[194:197], 0
	v_mfma_f32_16x16x32_bf16 v[14:17], v[150:153], v[202:205], 0
	v_mfma_f32_16x16x32_bf16 v[10:13], v[158:161], v[202:205], 0
	v_mfma_f32_16x16x32_bf16 v[6:9], v[150:153], v[216:219], 0
	v_mfma_f32_16x16x32_bf16 v[2:5], v[158:161], v[216:219], 0
	v_mfma_f32_16x16x32_bf16 v[46:49], v[154:157], v[190:193], v[46:49]
	v_mfma_f32_16x16x32_bf16 v[42:45], v[182:185], v[190:193], v[42:45]
	v_mfma_f32_16x16x32_bf16 v[30:33], v[154:157], v[198:201], v[30:33]
	v_mfma_f32_16x16x32_bf16 v[26:29], v[182:185], v[198:201], v[26:29]
	v_mfma_f32_16x16x32_bf16 v[14:17], v[154:157], v[212:215], v[14:17]
	v_mfma_f32_16x16x32_bf16 v[10:13], v[182:185], v[212:215], v[10:13]
	v_mfma_f32_16x16x32_bf16 v[6:9], v[154:157], v[220:223], v[6:9]
	v_mfma_f32_16x16x32_bf16 v[2:5], v[182:185], v[220:223], v[2:5]
	s_setprio 0
	s_barrier
	s_branch .Lpeel_mid_rs

.Lpeel_mid_rs:
	s_add_i32 s13, 0, 0x18000
	v_add_u32_e32 v1, s13, v208
	s_add_i32 s88, 0, 0x1c000
	ds_read_b128 v[134:137], v1
	ds_read_b128 v[138:141], v1 offset:1024
	ds_read_b128 v[142:145], v1 offset:2048
	ds_read_b128 v[146:149], v1 offset:3072
	v_add_u32_e32 v1, s88, v208
	ds_read_b128 v[150:153], v1
	ds_read_b128 v[154:157], v1 offset:1024
	ds_read_b128 v[158:161], v1 offset:2048
	ds_read_b128 v[182:185], v1 offset:3072
	s_add_u32 s76, s76, s56
	s_addc_u32 s77, s77, 0
	s_mov_b32 m0, s61
	v_lshl_add_u64 v[244:245], s[76:77], 0, v[166:167]
	ds_read_b128 v[186:189], v211 offset:32768
	ds_read_b128 v[190:193], v211 offset:33792
	ds_read_b128 v[194:197], v211 offset:34816
	ds_read_b128 v[198:201], v211 offset:35840
	ds_read_b128 v[202:205], v211 offset:36864
	ds_read_b128 v[212:215], v211 offset:37888
	ds_read_b128 v[216:219], v211 offset:38912
	ds_read_b128 v[220:223], v211 offset:39936
	global_load_lds_dwordx4 v[244:245], off
	v_lshl_add_u64 v[244:245], s[76:77], 0, v[170:171]
	s_mov_b32 m0, s83
	s_nop 0
	global_load_lds_dwordx4 v[244:245], off
	s_waitcnt vmcnt(8)
	s_waitcnt lgkmcnt(0)
	s_barrier
	s_setprio 1
	s_waitcnt lgkmcnt(0)
	v_mfma_f32_16x16x32_bf16 v[126:129], v[134:137], v[186:189], v[126:129]
	v_mfma_f32_16x16x32_bf16 v[122:125], v[142:145], v[186:189], v[122:125]
	v_mfma_f32_16x16x32_bf16 v[118:121], v[134:137], v[194:197], v[118:121]
	v_mfma_f32_16x16x32_bf16 v[114:117], v[142:145], v[194:197], v[114:117]
	v_mfma_f32_16x16x32_bf16 v[102:105], v[134:137], v[202:205], v[102:105]
	v_mfma_f32_16x16x32_bf16 v[98:101], v[142:145], v[202:205], v[98:101]
	v_mfma_f32_16x16x32_bf16 v[86:89], v[134:137], v[216:219], v[86:89]
	v_mfma_f32_16x16x32_bf16 v[82:85], v[142:145], v[216:219], v[82:85]
	v_mfma_f32_16x16x32_bf16 v[126:129], v[138:141], v[190:193], v[126:129]
	v_mfma_f32_16x16x32_bf16 v[122:125], v[146:149], v[190:193], v[122:125]
	v_mfma_f32_16x16x32_bf16 v[118:121], v[138:141], v[198:201], v[118:121]
	v_mfma_f32_16x16x32_bf16 v[114:117], v[146:149], v[198:201], v[114:117]
	v_mfma_f32_16x16x32_bf16 v[102:105], v[138:141], v[212:215], v[102:105]
	v_mfma_f32_16x16x32_bf16 v[98:101], v[146:149], v[212:215], v[98:101]
	v_mfma_f32_16x16x32_bf16 v[86:89], v[138:141], v[220:223], v[86:89]
	v_mfma_f32_16x16x32_bf16 v[82:85], v[146:149], v[220:223], v[82:85]
	s_setprio 0
	s_setprio 1
	v_mfma_f32_16x16x32_bf16 v[110:113], v[150:153], v[186:189], v[110:113]
	v_mfma_f32_16x16x32_bf16 v[106:109], v[158:161], v[186:189], v[106:109]
	v_mfma_f32_16x16x32_bf16 v[94:97], v[150:153], v[194:197], v[94:97]
	v_mfma_f32_16x16x32_bf16 v[90:93], v[158:161], v[194:197], v[90:93]
	v_mfma_f32_16x16x32_bf16 v[78:81], v[150:153], v[202:205], v[78:81]
	v_mfma_f32_16x16x32_bf16 v[74:77], v[158:161], v[202:205], v[74:77]
	v_mfma_f32_16x16x32_bf16 v[70:73], v[150:153], v[216:219], v[70:73]
	v_mfma_f32_16x16x32_bf16 v[66:69], v[158:161], v[216:219], v[66:69]
	v_mfma_f32_16x16x32_bf16 v[110:113], v[154:157], v[190:193], v[110:113]
	v_mfma_f32_16x16x32_bf16 v[106:109], v[182:185], v[190:193], v[106:109]
	v_mfma_f32_16x16x32_bf16 v[94:97], v[154:157], v[198:201], v[94:97]
	v_mfma_f32_16x16x32_bf16 v[90:93], v[182:185], v[198:201], v[90:93]
	v_mfma_f32_16x16x32_bf16 v[78:81], v[154:157], v[212:215], v[78:81]
	v_mfma_f32_16x16x32_bf16 v[74:77], v[182:185], v[212:215], v[74:77]
	v_mfma_f32_16x16x32_bf16 v[70:73], v[154:157], v[220:223], v[70:73]
	v_mfma_f32_16x16x32_bf16 v[66:69], v[182:185], v[220:223], v[66:69]
	s_setprio 0
	s_barrier
	s_add_i32 s13, s13, s97
	v_lshl_add_u64 v[224:225], v[224:225], 0, s[0:1]
	s_mov_b32 m0, s13
	ds_read_b128 v[186:189], v211 offset:49152
	ds_read_b128 v[190:193], v211 offset:50176
	ds_read_b128 v[194:197], v211 offset:51200
	ds_read_b128 v[198:201], v211 offset:52224
	ds_read_b128 v[202:205], v211 offset:53248
	ds_read_b128 v[212:215], v211 offset:54272
	ds_read_b128 v[216:219], v211 offset:55296
	ds_read_b128 v[220:223], v211 offset:56320
	global_load_lds_dwordx4 v[224:225], off
	v_lshl_add_u64 v[224:225], v[226:227], 0, s[0:1]
	s_add_i32 m0, s13, 0x2000
	s_add_i32 s13, s88, s97
	global_load_lds_dwordx4 v[224:225], off
	v_lshl_add_u64 v[224:225], v[228:229], 0, s[0:1]
	s_mov_b32 m0, s13
	s_nop 0
	global_load_lds_dwordx4 v[224:225], off
	v_lshl_add_u64 v[224:225], v[230:231], 0, s[0:1]
	s_add_i32 m0, s13, 0x2000
	s_nop 0
	global_load_lds_dwordx4 v[224:225], off
	v_lshl_add_u64 v[224:225], v[232:233], 0, s[0:1]
	s_mov_b32 m0, s2
	s_nop 0
	global_load_lds_dwordx4 v[224:225], off
	v_lshl_add_u64 v[224:225], v[242:243], 0, s[0:1]
	s_mov_b32 m0, s86
	s_nop 0
	global_load_lds_dwordx4 v[224:225], off
	s_waitcnt vmcnt(8)
	s_waitcnt lgkmcnt(0)
	s_barrier
	s_setprio 1
	s_waitcnt lgkmcnt(0)
	v_mfma_f32_16x16x32_bf16 v[62:65], v[134:137], v[186:189], v[62:65]
	v_mfma_f32_16x16x32_bf16 v[58:61], v[142:145], v[186:189], v[58:61]
	v_mfma_f32_16x16x32_bf16 v[54:57], v[134:137], v[194:197], v[54:57]
	v_mfma_f32_16x16x32_bf16 v[50:53], v[142:145], v[194:197], v[50:53]
	v_mfma_f32_16x16x32_bf16 v[38:41], v[134:137], v[202:205], v[38:41]
	v_mfma_f32_16x16x32_bf16 v[34:37], v[142:145], v[202:205], v[34:37]
	v_mfma_f32_16x16x32_bf16 v[22:25], v[134:137], v[216:219], v[22:25]
	v_mfma_f32_16x16x32_bf16 v[18:21], v[142:145], v[216:219], v[18:21]
	v_mfma_f32_16x16x32_bf16 v[62:65], v[138:141], v[190:193], v[62:65]
	v_mfma_f32_16x16x32_bf16 v[58:61], v[146:149], v[190:193], v[58:61]
	v_mfma_f32_16x16x32_bf16 v[54:57], v[138:141], v[198:201], v[54:57]
	v_mfma_f32_16x16x32_bf16 v[50:53], v[146:149], v[198:201], v[50:53]
	v_mfma_f32_16x16x32_bf16 v[38:41], v[138:141], v[212:215], v[38:41]
	v_mfma_f32_16x16x32_bf16 v[34:37], v[146:149], v[212:215], v[34:37]
	v_mfma_f32_16x16x32_bf16 v[22:25], v[138:141], v[220:223], v[22:25]
	v_mfma_f32_16x16x32_bf16 v[18:21], v[146:149], v[220:223], v[18:21]
	s_setprio 0
	s_setprio 1
	v_mfma_f32_16x16x32_bf16 v[46:49], v[150:153], v[186:189], v[46:49]
	v_mfma_f32_16x16x32_bf16 v[42:45], v[158:161], v[186:189], v[42:45]
	v_mfma_f32_16x16x32_bf16 v[30:33], v[150:153], v[194:197], v[30:33]
	v_mfma_f32_16x16x32_bf16 v[26:29], v[158:161], v[194:197], v[26:29]
	v_mfma_f32_16x16x32_bf16 v[14:17], v[150:153], v[202:205], v[14:17]
	v_mfma_f32_16x16x32_bf16 v[10:13], v[158:161], v[202:205], v[10:13]
	v_mfma_f32_16x16x32_bf16 v[6:9], v[150:153], v[216:219], v[6:9]
	v_mfma_f32_16x16x32_bf16 v[2:5], v[158:161], v[216:219], v[2:5]
	v_mfma_f32_16x16x32_bf16 v[46:49], v[154:157], v[190:193], v[46:49]
	v_mfma_f32_16x16x32_bf16 v[42:45], v[182:185], v[190:193], v[42:45]
	v_mfma_f32_16x16x32_bf16 v[30:33], v[154:157], v[198:201], v[30:33]
	v_mfma_f32_16x16x32_bf16 v[26:29], v[182:185], v[198:201], v[26:29]
	v_mfma_f32_16x16x32_bf16 v[14:17], v[154:157], v[212:215], v[14:17]
	v_mfma_f32_16x16x32_bf16 v[10:13], v[182:185], v[212:215], v[10:13]
	v_mfma_f32_16x16x32_bf16 v[6:9], v[154:157], v[220:223], v[6:9]
	v_mfma_f32_16x16x32_bf16 v[2:5], v[182:185], v[220:223], v[2:5]
	s_setprio 0
	s_barrier
	s_add_u32 s74, s74, 0x100
	s_addc_u32 s75, s75, 0
	s_add_u32 s67, s67, 0x100
	s_addc_u32 s73, s73, 0
	s_cmp_ge_i32 s12, s90
	s_cbranch_scc1 .LBB0_396

.LBB0_871:
	s_ashr_i32 s55, s54, 31
	s_lshl_b64 s[12:13], s[54:55], 19
	s_add_u32 s56, s8, s12
	s_addc_u32 s57, s9, s13
	s_and_b64 s[12:13], exec, s[42:43]
	s_cselect_b32 s7, s63, s57
	s_cselect_b32 s45, s62, s56
	s_ashr_i32 s53, s52, 31
	s_lshl_b64 s[12:13], s[52:53], 19
	s_add_u32 s58, s24, s12
	s_addc_u32 s59, s25, s13
	s_and_b64 s[12:13], exec, s[42:43]
	s_cselect_b32 s61, s65, s59
	s_cselect_b32 s75, s64, s58
	s_lshl_b64 s[12:13], s[54:55], 11
	v_lshl_add_u64 v[130:131], v[164:165], 0, s[12:13]
	s_lshl_b32 s12, s74, 12
	s_and_b32 s55, s12, 0x1000
	s_lshl_b64 s[12:13], s[52:53], 10
	v_lshl_add_u64 v[132:133], v[166:167], 0, s[12:13]
	v_readlane_b32 s12, v253, 43
	v_readlane_b32 s13, v253, 44
	s_or_b64 s[42:43], s[42:43], s[12:13]
	s_add_u32 s62, s62, 0x40080
	s_addc_u32 s63, s63, 0
	s_add_u32 s12, s64, 0x100
	s_addc_u32 s13, s65, 0
	s_mov_b32 s53, -2
	s_add_i32 s55, s73, s55
	s_mov_b64 s[64:65], -1
	s_add_u32 s66, s62, 0xfffc0080
	s_addc_u32 s67, s63, -1
	s_and_b64 s[64:65], s[64:65], exec
	s_cselect_b32 s67, s67, s7
	s_cselect_b32 s66, s66, s45
	s_cselect_b32 s65, s13, s61
	s_cselect_b32 s64, s12, s75
	s_add_i32 s76, 0, 0x10000
	s_add_i32 s78, 0, 0x14000
	v_add_u32_e32 v146, s76, v169
	v_add_u32_e32 v190, s78, v169
	ds_read_b128 v[134:137], v146
	ds_read_b128 v[138:141], v146 offset:1024
	ds_read_b128 v[142:145], v146 offset:2048
	ds_read_b128 v[146:149], v146 offset:3072
	ds_read_b128 v[150:153], v190
	ds_read_b128 v[182:185], v190 offset:1024
	ds_read_b128 v[186:189], v190 offset:2048
	ds_read_b128 v[190:193], v190 offset:3072
	v_lshl_add_u64 v[226:227], s[62:63], 0, v[178:179]
	s_add_i32 m0, s22, 0xc000
	ds_read_b128 v[194:197], v250
	ds_read_b128 v[198:201], v250 offset:1024
	ds_read_b128 v[202:205], v250 offset:2048
	ds_read_b128 v[206:209], v250 offset:3072
	ds_read_b128 v[210:213], v250 offset:4096
	ds_read_b128 v[214:217], v250 offset:5120
	ds_read_b128 v[218:221], v250 offset:6144
	ds_read_b128 v[222:225], v250 offset:7168
	global_load_lds_dwordx4 v[226:227], off
	v_lshl_add_u64 v[226:227], s[62:63], 0, v[180:181]
	s_add_i32 m0, s22, 0xe000
	s_nop 0
	global_load_lds_dwordx4 v[226:227], off
	s_waitcnt vmcnt(8)
	s_waitcnt lgkmcnt(0)
	s_barrier
	s_setprio 1
	s_waitcnt lgkmcnt(0)
	v_mfma_f32_16x16x32_bf16 v[62:65], v[134:137], v[194:197], 0
	v_mfma_f32_16x16x32_bf16 v[58:61], v[142:145], v[194:197], 0
	v_mfma_f32_16x16x32_bf16 v[54:57], v[134:137], v[202:205], 0
	v_mfma_f32_16x16x32_bf16 v[50:53], v[142:145], v[202:205], 0
	v_mfma_f32_16x16x32_bf16 v[46:49], v[134:137], v[210:213], 0
	v_mfma_f32_16x16x32_bf16 v[42:45], v[142:145], v[210:213], 0
	v_mfma_f32_16x16x32_bf16 v[38:41], v[134:137], v[218:221], 0
	v_mfma_f32_16x16x32_bf16 v[34:37], v[142:145], v[218:221], 0
	v_mfma_f32_16x16x32_bf16 v[62:65], v[138:141], v[198:201], v[62:65]
	v_mfma_f32_16x16x32_bf16 v[58:61], v[146:149], v[198:201], v[58:61]
	v_mfma_f32_16x16x32_bf16 v[54:57], v[138:141], v[206:209], v[54:57]
	v_mfma_f32_16x16x32_bf16 v[50:53], v[146:149], v[206:209], v[50:53]
	v_mfma_f32_16x16x32_bf16 v[46:49], v[138:141], v[214:217], v[46:49]
	v_mfma_f32_16x16x32_bf16 v[42:45], v[146:149], v[214:217], v[42:45]
	v_mfma_f32_16x16x32_bf16 v[38:41], v[138:141], v[222:225], v[38:41]
	v_mfma_f32_16x16x32_bf16 v[34:37], v[146:149], v[222:225], v[34:37]
	s_setprio 0
	s_setprio 1
	v_mfma_f32_16x16x32_bf16 v[126:129], v[150:153], v[194:197], 0
	v_mfma_f32_16x16x32_bf16 v[122:125], v[186:189], v[194:197], 0
	v_mfma_f32_16x16x32_bf16 v[118:121], v[150:153], v[202:205], 0
	v_mfma_f32_16x16x32_bf16 v[114:117], v[186:189], v[202:205], 0
	v_mfma_f32_16x16x32_bf16 v[110:113], v[150:153], v[210:213], 0
	v_mfma_f32_16x16x32_bf16 v[106:109], v[186:189], v[210:213], 0
	v_mfma_f32_16x16x32_bf16 v[102:105], v[150:153], v[218:221], 0
	v_mfma_f32_16x16x32_bf16 v[98:101], v[186:189], v[218:221], 0
	v_mfma_f32_16x16x32_bf16 v[126:129], v[182:185], v[198:201], v[126:129]
	v_mfma_f32_16x16x32_bf16 v[122:125], v[190:193], v[198:201], v[122:125]
	v_mfma_f32_16x16x32_bf16 v[118:121], v[182:185], v[206:209], v[118:121]
	v_mfma_f32_16x16x32_bf16 v[114:117], v[190:193], v[206:209], v[114:117]
	v_mfma_f32_16x16x32_bf16 v[110:113], v[182:185], v[214:217], v[110:113]
	v_mfma_f32_16x16x32_bf16 v[106:109], v[190:193], v[214:217], v[106:109]
	v_mfma_f32_16x16x32_bf16 v[102:105], v[182:185], v[222:225], v[102:105]
	v_mfma_f32_16x16x32_bf16 v[98:101], v[190:193], v[222:225], v[98:101]
	s_setprio 0
	s_barrier
	s_add_i32 s76, s76, s16
	v_lshl_add_u64 v[226:227], s[64:65], 0, v[156:157]
	s_mov_b32 m0, s76
	ds_read_b128 v[194:197], v250 offset:16384
	ds_read_b128 v[198:201], v250 offset:17408
	ds_read_b128 v[202:205], v250 offset:18432
	ds_read_b128 v[206:209], v250 offset:19456
	ds_read_b128 v[210:213], v250 offset:20480
	ds_read_b128 v[214:217], v250 offset:21504
	ds_read_b128 v[218:221], v250 offset:22528
	ds_read_b128 v[222:225], v250 offset:23552
	global_load_lds_dwordx4 v[226:227], off
	s_add_i32 m0, s76, 0x2000
	s_add_u32 s76, s64, 0x40000
	v_lshl_add_u64 v[228:229], s[64:65], 0, v[160:161]
	s_addc_u32 s77, s65, 0
	s_add_i32 s78, s78, s16
	global_load_lds_dwordx4 v[228:229], off
	v_lshl_add_u64 v[230:231], s[76:77], 0, v[156:157]
	s_mov_b32 m0, s78
	v_lshl_add_u64 v[232:233], s[66:67], 0, v[158:159]
	global_load_lds_dwordx4 v[230:231], off
	v_lshl_add_u64 v[230:231], s[76:77], 0, v[160:161]
	s_add_i32 m0, s78, 0x2000
	s_nop 0
	global_load_lds_dwordx4 v[230:231], off
	v_lshl_add_u64 v[230:231], s[66:67], 0, v[154:155]
	s_mov_b32 m0, s22
	s_nop 0
	global_load_lds_dwordx4 v[230:231], off
	s_mov_b32 m0, s23
	s_nop 0
	global_load_lds_dwordx4 v[232:233], off
	s_waitcnt vmcnt(8)
	s_waitcnt lgkmcnt(0)
	s_barrier
	s_setprio 1
	s_waitcnt lgkmcnt(0)
	v_mfma_f32_16x16x32_bf16 v[30:33], v[134:137], v[194:197], 0
	v_mfma_f32_16x16x32_bf16 v[26:29], v[142:145], v[194:197], 0
	v_mfma_f32_16x16x32_bf16 v[22:25], v[134:137], v[202:205], 0
	v_mfma_f32_16x16x32_bf16 v[18:21], v[142:145], v[202:205], 0
	v_mfma_f32_16x16x32_bf16 v[14:17], v[134:137], v[210:213], 0
	v_mfma_f32_16x16x32_bf16 v[10:13], v[142:145], v[210:213], 0
	v_mfma_f32_16x16x32_bf16 v[6:9], v[134:137], v[218:221], 0
	v_mfma_f32_16x16x32_bf16 v[2:5], v[142:145], v[218:221], 0
	v_mfma_f32_16x16x32_bf16 v[30:33], v[138:141], v[198:201], v[30:33]
	v_mfma_f32_16x16x32_bf16 v[26:29], v[146:149], v[198:201], v[26:29]
	v_mfma_f32_16x16x32_bf16 v[22:25], v[138:141], v[206:209], v[22:25]
	v_mfma_f32_16x16x32_bf16 v[18:21], v[146:149], v[206:209], v[18:21]
	v_mfma_f32_16x16x32_bf16 v[14:17], v[138:141], v[214:217], v[14:17]
	v_mfma_f32_16x16x32_bf16 v[10:13], v[146:149], v[214:217], v[10:13]
	v_mfma_f32_16x16x32_bf16 v[6:9], v[138:141], v[222:225], v[6:9]
	v_mfma_f32_16x16x32_bf16 v[2:5], v[146:149], v[222:225], v[2:5]
	s_setprio 0
	s_setprio 1
	v_mfma_f32_16x16x32_bf16 v[94:97], v[150:153], v[194:197], 0
	v_mfma_f32_16x16x32_bf16 v[90:93], v[186:189], v[194:197], 0
	v_mfma_f32_16x16x32_bf16 v[86:89], v[150:153], v[202:205], 0
	v_mfma_f32_16x16x32_bf16 v[82:85], v[186:189], v[202:205], 0
	v_mfma_f32_16x16x32_bf16 v[78:81], v[150:153], v[210:213], 0
	v_mfma_f32_16x16x32_bf16 v[74:77], v[186:189], v[210:213], 0
	v_mfma_f32_16x16x32_bf16 v[70:73], v[150:153], v[218:221], 0
	v_mfma_f32_16x16x32_bf16 v[66:69], v[186:189], v[218:221], 0
	v_mfma_f32_16x16x32_bf16 v[94:97], v[182:185], v[198:201], v[94:97]
	v_mfma_f32_16x16x32_bf16 v[90:93], v[190:193], v[198:201], v[90:93]
	v_mfma_f32_16x16x32_bf16 v[86:89], v[182:185], v[206:209], v[86:89]
	v_mfma_f32_16x16x32_bf16 v[82:85], v[190:193], v[206:209], v[82:85]
	v_mfma_f32_16x16x32_bf16 v[78:81], v[182:185], v[214:217], v[78:81]
	v_mfma_f32_16x16x32_bf16 v[74:77], v[190:193], v[214:217], v[74:77]
	v_mfma_f32_16x16x32_bf16 v[70:73], v[182:185], v[222:225], v[70:73]
	v_mfma_f32_16x16x32_bf16 v[66:69], v[190:193], v[222:225], v[66:69]
	s_setprio 0
	s_barrier
	s_branch .Lpeel_mid_st

.Lpeel_mid_st:
	s_add_i32 s76, 0, 0x18000
	s_add_i32 s77, 0, 0x1c000
	v_add_u32_e32 v146, s76, v169
	v_add_u32_e32 v190, s77, v169
	ds_read_b128 v[134:137], v146
	ds_read_b128 v[138:141], v146 offset:1024
	ds_read_b128 v[142:145], v146 offset:2048
	ds_read_b128 v[146:149], v146 offset:3072
	ds_read_b128 v[150:153], v190
	ds_read_b128 v[182:185], v190 offset:1024
	ds_read_b128 v[186:189], v190 offset:2048
	ds_read_b128 v[190:193], v190 offset:3072
	s_add_u32 s66, s66, 0x40000
	s_addc_u32 s67, s67, 0
	s_mov_b32 m0, s37
	v_lshl_add_u64 v[242:243], s[66:67], 0, v[154:155]
	ds_read_b128 v[194:197], v250 offset:32768
	ds_read_b128 v[198:201], v250 offset:33792
	ds_read_b128 v[202:205], v250 offset:34816
	ds_read_b128 v[206:209], v250 offset:35840
	ds_read_b128 v[210:213], v250 offset:36864
	ds_read_b128 v[214:217], v250 offset:37888
	ds_read_b128 v[218:221], v250 offset:38912
	ds_read_b128 v[222:225], v250 offset:39936
	global_load_lds_dwordx4 v[242:243], off
	v_lshl_add_u64 v[242:243], s[66:67], 0, v[158:159]
	s_mov_b32 m0, s68
	s_nop 0
	global_load_lds_dwordx4 v[242:243], off
	s_waitcnt vmcnt(8)
	s_waitcnt lgkmcnt(0)
	s_barrier
	s_setprio 1
	s_waitcnt lgkmcnt(0)
	v_mfma_f32_16x16x32_bf16 v[62:65], v[134:137], v[194:197], v[62:65]
	v_mfma_f32_16x16x32_bf16 v[58:61], v[142:145], v[194:197], v[58:61]
	v_mfma_f32_16x16x32_bf16 v[54:57], v[134:137], v[202:205], v[54:57]
	v_mfma_f32_16x16x32_bf16 v[50:53], v[142:145], v[202:205], v[50:53]
	v_mfma_f32_16x16x32_bf16 v[46:49], v[134:137], v[210:213], v[46:49]
	v_mfma_f32_16x16x32_bf16 v[42:45], v[142:145], v[210:213], v[42:45]
	v_mfma_f32_16x16x32_bf16 v[38:41], v[134:137], v[218:221], v[38:41]
	v_mfma_f32_16x16x32_bf16 v[34:37], v[142:145], v[218:221], v[34:37]
	v_mfma_f32_16x16x32_bf16 v[62:65], v[138:141], v[198:201], v[62:65]
	v_mfma_f32_16x16x32_bf16 v[58:61], v[146:149], v[198:201], v[58:61]
	v_mfma_f32_16x16x32_bf16 v[54:57], v[138:141], v[206:209], v[54:57]
	v_mfma_f32_16x16x32_bf16 v[50:53], v[146:149], v[206:209], v[50:53]
	v_mfma_f32_16x16x32_bf16 v[46:49], v[138:141], v[214:217], v[46:49]
	v_mfma_f32_16x16x32_bf16 v[42:45], v[146:149], v[214:217], v[42:45]
	v_mfma_f32_16x16x32_bf16 v[38:41], v[138:141], v[222:225], v[38:41]
	v_mfma_f32_16x16x32_bf16 v[34:37], v[146:149], v[222:225], v[34:37]
	s_setprio 0
	s_setprio 1
	v_mfma_f32_16x16x32_bf16 v[126:129], v[150:153], v[194:197], v[126:129]
	v_mfma_f32_16x16x32_bf16 v[122:125], v[186:189], v[194:197], v[122:125]
	v_mfma_f32_16x16x32_bf16 v[118:121], v[150:153], v[202:205], v[118:121]
	v_mfma_f32_16x16x32_bf16 v[114:117], v[186:189], v[202:205], v[114:117]
	v_mfma_f32_16x16x32_bf16 v[110:113], v[150:153], v[210:213], v[110:113]
	v_mfma_f32_16x16x32_bf16 v[106:109], v[186:189], v[210:213], v[106:109]
	v_mfma_f32_16x16x32_bf16 v[102:105], v[150:153], v[218:221], v[102:105]
	v_mfma_f32_16x16x32_bf16 v[98:101], v[186:189], v[218:221], v[98:101]
	v_mfma_f32_16x16x32_bf16 v[126:129], v[182:185], v[198:201], v[126:129]
	v_mfma_f32_16x16x32_bf16 v[122:125], v[190:193], v[198:201], v[122:125]
	v_mfma_f32_16x16x32_bf16 v[118:121], v[182:185], v[206:209], v[118:121]
	v_mfma_f32_16x16x32_bf16 v[114:117], v[190:193], v[206:209], v[114:117]
	v_mfma_f32_16x16x32_bf16 v[110:113], v[182:185], v[214:217], v[110:113]
	v_mfma_f32_16x16x32_bf16 v[106:109], v[190:193], v[214:217], v[106:109]
	v_mfma_f32_16x16x32_bf16 v[102:105], v[182:185], v[222:225], v[102:105]
	v_mfma_f32_16x16x32_bf16 v[98:101], v[190:193], v[222:225], v[98:101]
	s_setprio 0
	s_barrier
	s_add_i32 s66, s76, s16
	v_lshl_add_u64 v[226:227], v[226:227], 0, s[0:1]
	s_mov_b32 m0, s66
	ds_read_b128 v[194:197], v250 offset:49152
	ds_read_b128 v[198:201], v250 offset:50176
	ds_read_b128 v[202:205], v250 offset:51200
	ds_read_b128 v[206:209], v250 offset:52224
	ds_read_b128 v[210:213], v250 offset:53248
	ds_read_b128 v[214:217], v250 offset:54272
	ds_read_b128 v[218:221], v250 offset:55296
	ds_read_b128 v[222:225], v250 offset:56320
	global_load_lds_dwordx4 v[226:227], off
	s_add_i32 m0, s66, 0x2000
	s_add_u32 s64, s64, 0x40080
	v_lshl_add_u64 v[226:227], v[228:229], 0, s[0:1]
	s_addc_u32 s65, s65, 0
	s_add_i32 s66, s77, s16
	global_load_lds_dwordx4 v[226:227], off
	v_lshl_add_u64 v[226:227], s[64:65], 0, v[156:157]
	s_mov_b32 m0, s66
	s_nop 0
	global_load_lds_dwordx4 v[226:227], off
	v_lshl_add_u64 v[226:227], s[64:65], 0, v[160:161]
	s_add_i32 m0, s66, 0x2000
	s_nop 0
	global_load_lds_dwordx4 v[226:227], off
	v_lshl_add_u64 v[226:227], v[230:231], 0, s[0:1]
	s_mov_b32 m0, s71
	s_nop 0
	global_load_lds_dwordx4 v[226:227], off
	v_lshl_add_u64 v[226:227], v[232:233], 0, s[0:1]
	s_mov_b32 m0, s72
	s_nop 0
	global_load_lds_dwordx4 v[226:227], off
	s_waitcnt vmcnt(8)
	s_waitcnt lgkmcnt(0)
	s_barrier
	s_setprio 1
	s_waitcnt lgkmcnt(0)
	v_mfma_f32_16x16x32_bf16 v[30:33], v[134:137], v[194:197], v[30:33]
	v_mfma_f32_16x16x32_bf16 v[26:29], v[142:145], v[194:197], v[26:29]
	v_mfma_f32_16x16x32_bf16 v[22:25], v[134:137], v[202:205], v[22:25]
	v_mfma_f32_16x16x32_bf16 v[18:21], v[142:145], v[202:205], v[18:21]
	v_mfma_f32_16x16x32_bf16 v[14:17], v[134:137], v[210:213], v[14:17]
	v_mfma_f32_16x16x32_bf16 v[10:13], v[142:145], v[210:213], v[10:13]
	v_mfma_f32_16x16x32_bf16 v[6:9], v[134:137], v[218:221], v[6:9]
	v_mfma_f32_16x16x32_bf16 v[2:5], v[142:145], v[218:221], v[2:5]
	v_mfma_f32_16x16x32_bf16 v[30:33], v[138:141], v[198:201], v[30:33]
	v_mfma_f32_16x16x32_bf16 v[26:29], v[146:149], v[198:201], v[26:29]
	v_mfma_f32_16x16x32_bf16 v[22:25], v[138:141], v[206:209], v[22:25]
	v_mfma_f32_16x16x32_bf16 v[18:21], v[146:149], v[206:209], v[18:21]
	v_mfma_f32_16x16x32_bf16 v[14:17], v[138:141], v[214:217], v[14:17]
	v_mfma_f32_16x16x32_bf16 v[10:13], v[146:149], v[214:217], v[10:13]
	v_mfma_f32_16x16x32_bf16 v[6:9], v[138:141], v[222:225], v[6:9]
	v_mfma_f32_16x16x32_bf16 v[2:5], v[146:149], v[222:225], v[2:5]
	s_setprio 0
	s_setprio 1
	v_mfma_f32_16x16x32_bf16 v[94:97], v[150:153], v[194:197], v[94:97]
	v_mfma_f32_16x16x32_bf16 v[90:93], v[186:189], v[194:197], v[90:93]
	v_mfma_f32_16x16x32_bf16 v[86:89], v[150:153], v[202:205], v[86:89]
	v_mfma_f32_16x16x32_bf16 v[82:85], v[186:189], v[202:205], v[82:85]
	v_mfma_f32_16x16x32_bf16 v[78:81], v[150:153], v[210:213], v[78:81]
	v_mfma_f32_16x16x32_bf16 v[74:77], v[186:189], v[210:213], v[74:77]
	v_mfma_f32_16x16x32_bf16 v[70:73], v[150:153], v[218:221], v[70:73]
	v_mfma_f32_16x16x32_bf16 v[66:69], v[186:189], v[218:221], v[66:69]
	v_mfma_f32_16x16x32_bf16 v[94:97], v[182:185], v[198:201], v[94:97]
	v_mfma_f32_16x16x32_bf16 v[90:93], v[190:193], v[198:201], v[90:93]
	v_mfma_f32_16x16x32_bf16 v[86:89], v[182:185], v[206:209], v[86:89]
	v_mfma_f32_16x16x32_bf16 v[82:85], v[190:193], v[206:209], v[82:85]
	v_mfma_f32_16x16x32_bf16 v[78:81], v[182:185], v[214:217], v[78:81]
	v_mfma_f32_16x16x32_bf16 v[74:77], v[190:193], v[214:217], v[74:77]
	v_mfma_f32_16x16x32_bf16 v[70:73], v[182:185], v[222:225], v[70:73]
	v_mfma_f32_16x16x32_bf16 v[66:69], v[190:193], v[222:225], v[66:69]
	s_setprio 0
	s_barrier
	s_add_i32 s53, s53, 2
	s_add_u32 s62, s62, 0x100
	s_addc_u32 s63, s63, 0
	s_add_u32 s12, s12, 0x100
	s_addc_u32 s13, s13, 0
	s_cmp_gt_u32 s53, 13
	s_cbranch_scc1 .LBB0_875
